# sample memory-attention units: each wave touches the next unit's K/V tile lines (one L2-warming dword load per lane) behind its own loads
# baseline (speedup 1.0000x reference)
.LBB0_823:
	s_cmp_lt_i32 s24, s25
	v_readlane_b32 s2, v254, 46
	v_readlane_b32 s3, v254, 62
	s_cselect_b32 s13, s2, s3
	s_add_i32 s13, s13, s24
	v_mov_b32_e32 v83, v170
	s_cmpk_gt_i32 s13, 0xff
	v_bfe_u32 v88, v83, 5, 1
	v_lshlrev_b32_e32 v173, 2, v88
	v_lshrrev_b32_e32 v0, 2, v83
	s_cselect_b64 s[30:31], -1, 0
	s_cmpk_lt_u32 s13, 0x400
	v_and_or_b32 v0, v0, 3, v173
	s_cselect_b32 s2, 2, 3
	s_cmpk_gt_u32 s13, 0x2ff
	v_and_b32_e32 v87, 31, v83
	v_mul_u32_u24_e32 v86, 0x90, v0
	v_and_b32_e32 v89, 16, v83
	s_cselect_b32 s10, s2, 1
	s_and_b64 vcc, exec, s[30:31]
	s_cbranch_vccz .LBB0_883
	s_cmp_lt_i32 s10, 2
	v_and_b32_e32 v82, 63, v83
	s_cbranch_scc1 .LBB0_884
	s_cmp_lg_u32 s10, 2
	s_mov_b64 s[4:5], -1
	s_cbranch_scc0 .LBB0_836
	v_readlane_b32 s2, v255, 8
	v_readlane_b32 s3, v255, 9
	s_add_i32 s7, s13, 0xfffffc00
	s_andn2_b64 vcc, exec, s[2:3]
	s_and_b32 s6, s13, 3
	s_cbranch_vccnz .LBB0_832
	s_and_b32 s4, s7, -4
	v_or_b32_e32 v0, 0x4000, v87
	v_cmp_gt_u32_e32 vcc, 4, v87
	v_mov_b32_e32 v2, 0x4000
	s_ashr_i32 s5, s4, 31
	v_cndmask_b32_e32 v0, v2, v0, vcc
	s_ashr_i32 s2, s7, 2
	v_lshl_add_u64 v[2:3], v[0:1], 0, s[4:5]
	v_readlane_b32 s4, v255, 14
	v_lshlrev_b64 v[2:3], 9, v[2:3]
	v_readlane_b32 s5, v255, 15
	s_ashr_i32 s3, s2, 31
	s_lshl_b32 s16, s6, 7
	v_lshl_add_u64 v[2:3], s[4:5], 0, v[2:3]
	s_lshl_b64 s[2:3], s[2:3], 16
	v_readlane_b32 s4, v255, 4
	v_readlane_b32 s5, v255, 5
	s_add_u32 s2, s2, s4
	s_addc_u32 s3, s3, s5
	s_lshl_b64 s[2:3], s[2:3], 2
	v_readlane_b32 s4, v254, 52
	s_add_u32 s4, s4, s2
	v_readlane_b32 s5, v254, 53
	s_addc_u32 s5, s5, s3
	s_lshl_b32 s8, s6, 8
	v_lshl_add_u64 v[2:3], v[2:3], 0, s[16:17]
	v_lshlrev_b32_e32 v0, 4, v88
	s_add_u32 s4, s4, s8
	v_lshl_add_u64 v[78:79], v[2:3], 0, v[0:1]
	s_addc_u32 s5, s5, 0
	v_lshlrev_b32_e32 v0, 10, v87
	v_lshl_add_u64 v[6:7], s[4:5], 0, v[0:1]
	v_lshlrev_b32_e32 v0, 5, v88
	v_lshl_add_u64 v[42:43], v[6:7], 0, v[0:1]
	global_load_dwordx4 v[2:5], v[78:79], off
	global_load_dwordx4 v[18:21], v[78:79], off offset:32
	global_load_dwordx4 v[22:25], v[78:79], off offset:64
	global_load_dwordx4 v[6:9], v[42:43], off offset:16
	global_load_dwordx4 v[10:13], v[42:43], off
	global_load_dwordx4 v[14:17], v[42:43], off offset:80
	global_load_dwordx4 v[26:29], v[42:43], off offset:64
	global_load_dwordx4 v[30:33], v[42:43], off offset:144
	global_load_dwordx4 v[34:37], v[42:43], off offset:128
	global_load_dwordx4 v[38:41], v[42:43], off offset:208
	s_nop 0
	global_load_dwordx4 v[42:45], v[42:43], off offset:192
	v_readlane_b32 s98, v254, 44
	v_readlane_b32 s99, v254, 48
	s_sub_i32 s99, s99, s98
	s_lshl_b32 s98, s98, 16
	s_cmp_lt_i32 s24, s99
	s_cselect_b32 s98, s98, 0
	v_lshlrev_b32_e32 v100, 10, v87
	v_lshl_or_b32 v100, v88, 7, v100
	v_add_u32_e32 v100, s98, v100
	v_mov_b32_e32 v101, 0
	v_lshl_add_u64 v[102:103], s[4:5], 0, v[100:101]
	v_readlane_b32 s9, v254, 54
	s_add_u32 s2, s9, s2
	v_readlane_b32 s9, v254, 55
	s_addc_u32 s3, s9, s3
	s_add_u32 s2, s2, s8
	v_lshlrev_b32_e32 v0, 4, v82
	s_addc_u32 s3, s3, 0
	v_lshl_add_u64 v[104:105], s[2:3], 0, v[100:101]
	v_and_b32_e32 v0, 0xf0, v0
	v_lshl_add_u64 v[46:47], s[2:3], 0, v[0:1]
	v_lshlrev_b32_e32 v0, 6, v82
	v_and_b32_e32 v0, 0xc00, v0
	v_lshl_add_u64 v[74:75], v[46:47], 0, v[0:1]
	v_add_co_u32_e64 v54, s[2:3], s80, v74
	global_load_dwordx4 v[46:49], v[74:75], off nt
	s_nop 0
	v_addc_co_u32_e64 v55, s[2:3], 0, v75, s[2:3]
	v_add_co_u32_e64 v62, s[2:3], s81, v74
	global_load_dwordx4 v[50:53], v[54:55], off offset:-4096 nt
	s_nop 0
	global_load_dwordx4 v[54:57], v[54:55], off nt
	v_addc_co_u32_e64 v63, s[2:3], 0, v75, s[2:3]
	s_movk_i32 s2, 0x6000
	s_nop 0
	v_add_co_u32_e64 v70, s[2:3], s2, v74
	global_load_dwordx4 v[58:61], v[62:63], off offset:-4096 nt
	s_nop 0
	global_load_dwordx4 v[62:65], v[62:63], off nt
	v_addc_co_u32_e64 v71, s[2:3], 0, v75, s[2:3]
	s_movk_i32 s2, 0x7000
	s_nop 0
	v_add_co_u32_e64 v74, s[2:3], s2, v74
	global_load_dwordx4 v[66:69], v[70:71], off offset:-4096 nt
	s_nop 0
	global_load_dwordx4 v[70:73], v[70:71], off nt
	v_addc_co_u32_e64 v75, s[2:3], 0, v75, s[2:3]
	global_load_dwordx4 v[74:77], v[74:75], off nt
	s_nop 0
	global_load_dwordx4 v[78:81], v[78:79], off offset:96
	global_load_dword v106, v[102:103], off
	global_load_dword v106, v[104:105], off
	v_lshlrev_b32_e32 v0, 3, v82
	v_lshrrev_b32_e32 v85, 4, v82
	v_and_b32_e32 v0, 0x78, v0
	v_mul_u32_u24_e32 v85, 0x90, v85
	v_readlane_b32 s9, v254, 63
	s_mov_b32 s8, 0xefa18f08
	v_lshlrev_b32_e32 v84, 2, v82
	v_add3_u32 v0, s9, v0, v85
	v_add_u32_e32 v85, 0x800, v0
	s_waitcnt vmcnt(17)
	v_cvt_pk_bf16_f32 v10, v10, v11
	v_cvt_pk_bf16_f32 v11, v12, v13
	v_cvt_pk_bf16_f32 v12, v6, v7
	v_cvt_pk_bf16_f32 v13, v8, v9
	s_waitcnt vmcnt(15)
	v_cvt_pk_bf16_f32 v26, v26, v27
	v_cvt_pk_bf16_f32 v27, v28, v29
	v_cvt_pk_bf16_f32 v28, v14, v15
	v_cvt_pk_bf16_f32 v29, v16, v17
	v_mfma_f32_32x32x16_bf16 v[2:17], v[10:13], v[2:5], 0
	s_waitcnt vmcnt(13)
	v_cvt_pk_bf16_f32 v34, v34, v35
	v_cvt_pk_bf16_f32 v35, v36, v37
	v_cvt_pk_bf16_f32 v36, v30, v31
	v_cvt_pk_bf16_f32 v37, v32, v33
	s_waitcnt vmcnt(11)
	v_cvt_pk_bf16_f32 v30, v42, v43
	v_cvt_pk_bf16_f32 v31, v44, v45
	v_cvt_pk_bf16_f32 v32, v38, v39
	v_mfma_f32_32x32x16_bf16 v[2:17], v[26:29], v[18:21], v[2:17]
	v_cvt_pk_bf16_f32 v33, v40, v41
	s_waitcnt vmcnt(10)
	v_cvt_pk_bf16_f32 v38, v46, v47
	v_cvt_pk_bf16_f32 v39, v48, v49
	s_waitcnt vmcnt(9)
	v_cvt_pk_bf16_f32 v40, v50, v51
	v_mfma_f32_32x32x16_bf16 v[2:17], v[34:37], v[22:25], v[2:17]
	v_cvt_pk_bf16_f32 v41, v52, v53
	s_waitcnt vmcnt(8)
	v_cvt_pk_bf16_f32 v18, v54, v55
	v_cvt_pk_bf16_f32 v19, v56, v57
	s_waitcnt vmcnt(7)
	v_cvt_pk_bf16_f32 v20, v58, v59
	v_cvt_pk_bf16_f32 v21, v60, v61
	ds_write2_b64 v0, v[38:39], v[40:41] offset1:72
	ds_write2_b64 v0, v[18:19], v[20:21] offset0:144 offset1:216
	s_waitcnt vmcnt(2)
	v_mfma_f32_32x32x16_bf16 v[2:17], v[30:33], v[78:81], v[2:17]
	v_cvt_pk_bf16_f32 v26, v62, v63
	v_cvt_pk_bf16_f32 v27, v64, v65
	v_cvt_pk_bf16_f32 v28, v66, v67
	v_cvt_pk_bf16_f32 v29, v68, v69
	v_cvt_pk_bf16_f32 v22, v70, v71
	v_cvt_pk_bf16_f32 v23, v72, v73
	v_cvt_pk_bf16_f32 v24, v74, v75
	s_nop 4
	v_pk_mul_f32 v[2:3], v[2:3], s[28:29] op_sel_hi:[1,0]
	v_pk_mul_f32 v[4:5], v[4:5], s[28:29] op_sel_hi:[1,0]
	v_max3_f32 v0, v2, s86, v3
	v_pk_mul_f32 v[6:7], v[6:7], s[28:29] op_sel_hi:[1,0]
	v_max3_f32 v0, v0, v4, v5
	v_pk_mul_f32 v[8:9], v[8:9], s[28:29] op_sel_hi:[1,0]
	v_max3_f32 v0, v0, v6, v7
	v_pk_mul_f32 v[10:11], v[10:11], s[28:29] op_sel_hi:[1,0]
	v_max3_f32 v0, v0, v8, v9
	v_pk_mul_f32 v[12:13], v[12:13], s[28:29] op_sel_hi:[1,0]
	v_max3_f32 v0, v0, v10, v11
	v_pk_mul_f32 v[14:15], v[14:15], s[28:29] op_sel_hi:[1,0]
	v_max3_f32 v0, v0, v12, v13
	v_pk_mul_f32 v[38:39], v[16:17], s[28:29] op_sel_hi:[1,0]
	v_max3_f32 v0, v0, v14, v15
	v_max3_f32 v0, v0, v38, v39
	ds_bpermute_b32 v16, v171, v0
	v_cmp_lt_f32_e64 s[2:3], s8, v3
	v_cmp_lt_f32_e64 s[4:5], s8, v2
	v_cvt_pk_bf16_f32 v25, v76, v77
	ds_write2_b64 v85, v[26:27], v[28:29] offset0:32 offset1:104
	ds_write2_b64 v85, v[22:23], v[24:25] offset0:176 offset1:248
	s_waitcnt lgkmcnt(2)
	v_max_f32_e32 v16, v16, v16
	v_max_f32_e32 v0, v0, v16
	v_sub_f32_e32 v3, v3, v0
	v_sub_f32_e32 v17, v5, v0
	v_exp_f32_e32 v3, v3
	v_exp_f32_e32 v17, v17
	v_sub_f32_e32 v16, v4, v0
	v_exp_f32_e32 v16, v16
	v_cndmask_b32_e64 v18, 0, v3, s[2:3]
	v_cmp_lt_f32_e64 s[2:3], s8, v5
	v_sub_f32_e32 v3, v7, v0
	v_exp_f32_e32 v3, v3
	v_cndmask_b32_e64 v17, 0, v17, s[2:3]
	v_cmp_lt_f32_e64 s[2:3], s8, v4
	v_sub_f32_e32 v4, v6, v0
	v_exp_f32_e32 v4, v4
	v_sub_f32_e32 v2, v2, v0
	v_exp_f32_e32 v2, v2
	v_cndmask_b32_e64 v16, 0, v16, s[2:3]
	v_cmp_lt_f32_e64 s[2:3], s8, v7
	v_cvt_pk_bf16_f32 v7, v16, v17
	v_cndmask_b32_e64 v19, 0, v2, s[4:5]
	v_cndmask_b32_e64 v20, 0, v3, s[2:3]
	v_cmp_lt_f32_e64 s[2:3], s8, v6
	v_sub_f32_e32 v3, v9, v0
	v_exp_f32_e32 v3, v3
	v_cndmask_b32_e64 v21, 0, v4, s[2:3]
	v_sub_f32_e32 v4, v8, v0
	v_exp_f32_e32 v4, v4
	v_add_f32_e32 v2, 0, v19
	v_cmp_lt_f32_e64 s[2:3], s8, v9
	v_add_f32_e32 v2, v18, v2
	v_add_f32_e32 v2, v16, v2
	v_cndmask_b32_e64 v9, 0, v3, s[2:3]
	v_cmp_lt_f32_e64 s[2:3], s8, v8
	v_sub_f32_e32 v3, v11, v0
	v_exp_f32_e32 v3, v3
	v_cndmask_b32_e64 v22, 0, v4, s[2:3]
	v_sub_f32_e32 v4, v10, v0
	v_add_f32_e32 v2, v17, v2
	v_exp_f32_e32 v4, v4
	v_add_f32_e32 v2, v21, v2
	v_add_f32_e32 v2, v20, v2
	v_cmp_lt_f32_e64 s[2:3], s8, v11
	v_add_f32_e32 v2, v22, v2
	v_add_f32_e32 v2, v9, v2
	v_cndmask_b32_e64 v40, 0, v3, s[2:3]
	v_cmp_lt_f32_e64 s[2:3], s8, v10
	v_sub_f32_e32 v3, v12, v0
	v_exp_f32_e32 v3, v3
	v_cndmask_b32_e64 v41, 0, v4, s[2:3]
	v_add_f32_e32 v2, v41, v2
	v_add_f32_e32 v46, v40, v2
	v_sub_f32_e32 v2, v13, v0
	v_exp_f32_e32 v2, v2
	v_cmp_lt_f32_e64 s[2:3], s8, v13
	v_cvt_pk_bf16_f32 v8, v21, v20
	v_cvt_pk_bf16_f32 v9, v22, v9
	v_cndmask_b32_e64 v47, 0, v2, s[2:3]
	v_sub_f32_e32 v2, v14, v0
	v_exp_f32_e32 v34, v2
	v_sub_f32_e32 v2, v15, v0
	v_exp_f32_e32 v6, v2
	v_and_or_b32 v2, v84, 12, v89
	v_lshlrev_b32_e32 v2, 1, v2
	v_cmp_lt_f32_e64 s[2:3], s8, v12
	v_add3_u32 v42, s9, v86, v2
	s_nop 0
	v_cndmask_b32_e64 v48, 0, v3, s[2:3]
	ds_read_b64_tr_b16 v[2:3], v42
	ds_read_b64_tr_b16 v[4:5], v42 offset:1152
	v_cmp_lt_f32_e64 s[2:3], s8, v15
	ds_read_b64_tr_b16 v[12:13], v42 offset:1216
	ds_read_b64_tr_b16 v[10:11], v42 offset:64
	v_cndmask_b32_e64 v49, 0, v6, s[2:3]
	v_cvt_pk_bf16_f32 v6, v19, v18
	v_cmp_lt_f32_e64 s[2:3], s8, v14
	s_waitcnt lgkmcnt(2)
	v_mfma_f32_32x32x16_bf16 v[18:33], v[2:5], v[6:9], 0
	v_sub_f32_e32 v2, v39, v0
	v_exp_f32_e32 v2, v2
	v_sub_f32_e32 v3, v38, v0
	v_cndmask_b32_e64 v50, 0, v34, s[2:3]
	v_exp_f32_e32 v43, v3
	v_cmp_lt_f32_e64 s[2:3], s8, v39
	ds_read_b64_tr_b16 v[34:35], v42 offset:2304
	ds_read_b64_tr_b16 v[36:37], v42 offset:3456
	v_cndmask_b32_e64 v51, 0, v2, s[2:3]
	s_waitcnt lgkmcnt(2)
	v_mfma_f32_32x32x16_bf16 v[2:17], v[10:13], v[6:9], 0
	v_cmp_lt_f32_e64 s[2:3], s8, v38
	v_cvt_pk_bf16_f32 v38, v41, v40
	v_cvt_pk_bf16_f32 v39, v48, v47
	v_cndmask_b32_e64 v52, 0, v43, s[2:3]
	ds_read_b64_tr_b16 v[44:45], v42 offset:3520
	ds_read_b64_tr_b16 v[42:43], v42 offset:2368
	v_cvt_pk_bf16_f32 v40, v50, v49
	v_cvt_pk_bf16_f32 v41, v52, v51
	s_waitcnt lgkmcnt(2)
	s_nop 0
	v_mfma_f32_32x32x16_bf16 v[18:33], v[34:37], v[38:41], v[18:33]
	v_add_f32_e32 v34, v48, v46
	v_add_f32_e32 v34, v47, v34
	v_add_f32_e32 v34, v50, v34
	v_add_f32_e32 v34, v49, v34
	v_add_f32_e32 v34, v52, v34
	v_add_f32_e32 v34, v51, v34
	ds_bpermute_b32 v35, v171, v34
	s_waitcnt lgkmcnt(1)
	v_mfma_f32_32x32x16_bf16 v[2:17], v[42:45], v[38:41], v[2:17]
	s_and_saveexec_b64 s[2:3], vcc
	s_cbranch_execz .LBB0_831
	v_cmp_gt_u32_e32 vcc, 32, v82
	s_and_saveexec_b64 s[4:5], vcc
	s_cbranch_execz .LBB0_830
	v_readlane_b32 s8, v255, 6
	s_waitcnt lgkmcnt(0)
	v_add_f32_e32 v34, v34, v35
	v_or_b32_e32 v35, s8, v87
	v_lshl_add_u32 v35, v35, 2, 0
	ds_write2st64_b32 v35, v0, v34 offset0:144 offset1:146
